# MLA latent attention loop: per-tile LDS-DMA address arithmetic (22 VALU incl. 64-bit adds/muls) replaced by per-unit lane offsets v208-212 + scalar K/V tile bases in s[4:5]/s[34:35], saddr-form global
# speedup vs baseline: 1.0462x; 1.0035x over previous
.LBB0_510:
	s_and_b64 vcc, exec, s[4:5]
	s_cbranch_vccz .LBB0_498
	s_lshl_b32 s0, s11, 2
	s_lshr_b32 s1, s18, 4
	s_lshr_b32 s4, s11, 1
	s_and_b32 s0, s0, 4
	v_readlane_b32 s16, v254, 44
	s_or_b32 s19, s1, s0
	s_lshl_b32 s0, s4, 12
	v_readlane_b32 s17, v254, 45
	s_mov_b32 s31, s17
	s_add_i32 s30, s0, 0x2000
	s_lshl_b32 s0, s18, 8
	s_and_b32 s29, s0, 0xf00
	s_lshl_b64 s[0:1], s[30:31], 3
	s_or_b32 s0, s0, s19
	s_mul_i32 s5, s0, 0x180
	s_mul_hi_u32 s0, s0, 0x180
	s_mulk_i32 s1, 0x180
	s_or_b32 s20, s29, s30
	s_add_i32 s0, s0, s1
	v_readlane_b32 s25, v254, 38
	s_add_u32 s16, s25, s5
	v_readlane_b32 s26, v254, 39
	s_addc_u32 s17, s26, s0
	s_lshl_b64 s[0:1], s[30:31], 12
	v_readlane_b32 s27, v254, 40
	s_add_u32 s0, s27, s0
	v_readlane_b32 s28, v254, 41
	s_addc_u32 s1, s28, s1
	s_lshl_b32 s21, s19, 7
	s_lshl_b32 s18, s19, 8
	s_add_u32 s0, s0, s18
	s_addc_u32 s1, s1, 0
	s_add_u32 s23, s0, 0x800
	s_addc_u32 s24, s1, 0
	s_lshl_b32 s4, s4, 9
	s_add_i32 s30, s4, 0x6000
	s_lshl_b64 s[4:5], s[30:31], 3
	s_or_b32 s4, s4, s19
	s_mul_i32 s22, s4, 0x180
	s_mul_hi_u32 s4, s4, 0x180
	s_mulk_i32 s5, 0x180
	s_add_i32 s4, s4, s5
	s_add_u32 s25, s25, s22
	s_addc_u32 s26, s26, s4
	s_lshl_b64 s[4:5], s[30:31], 12
	s_add_u32 s4, s27, s4
	s_addc_u32 s5, s28, s5
	s_add_u32 s4, s4, s18
	s_addc_u32 s5, s5, 0
	s_add_u32 s27, s4, 0x800
	s_addc_u32 s28, s5, 0
	s_mul_i32 s5, s20, 0x8200
	s_mul_hi_u32 s4, s20, 0x8200
	s_add_u32 s18, s39, s5
	v_readlane_b32 s5, v254, 24
	s_addc_u32 s22, s5, s4
	s_mov_b32 s5, s31
	s_mul_i32 s30, s19, 0xc0
	v_writelane_b32 v254, s4, 44
	v_mov_b32_e32 v201, v0
	v_mov_b32_e32 v13, v3
	v_writelane_b32 v254, s5, 45
	s_lshl_b64 s[4:5], s[30:31], 1
	s_add_u32 s18, s18, s4
	v_readfirstlane_b32 s4, v201
	s_addc_u32 s19, s22, s5
	s_ashr_i32 s5, s4, 6
	v_and_b32_e32 v149, 31, v201
	s_lshl_b32 s22, s5, 5
	v_bfe_u32 v1, v201, 5, 1
	v_or_b32_e32 v2, s22, v149
	v_mov_b64_e32 v[4:5], s[18:19]
	v_mad_i64_i32 v[4:5], s[18:19], v2, s36, v[4:5]
	v_lshlrev_b32_e32 v2, 4, v1
	v_lshl_add_u64 v[4:5], v[4:5], 0, v[2:3]
	global_load_dwordx4 v[128:131], v[4:5], off offset:320
	global_load_dwordx4 v[140:143], v[4:5], off offset:352
	global_load_dwordx4 v[164:167], v[4:5], off offset:256
	global_load_dwordx4 v[172:175], v[4:5], off offset:288
	global_load_dwordx4 v[116:119], v[4:5], off
	global_load_dwordx4 v[120:123], v[4:5], off offset:32
	global_load_dwordx4 v[220:223], v[4:5], off offset:64
	global_load_dwordx4 v[212:215], v[4:5], off offset:96
	global_load_dwordx4 v[182:185], v[4:5], off offset:224
	global_load_dwordx4 v[186:189], v[4:5], off offset:192
	global_load_dwordx4 v[204:207], v[4:5], off offset:128
	global_load_dwordx4 v[190:193], v[4:5], off offset:160
	v_or_b32_e32 v14, s29, v149
	v_and_b32_e32 v12, 32, v201
	v_add_u32_e32 v126, s22, v14
	global_load_dwordx4 v[112:115], v12, s[42:43]
	global_load_dwordx4 v[100:103], v12, s[42:43] offset:16
	global_load_dwordx4 v[108:111], v12, s[42:43] offset:64
	global_load_dwordx4 v[104:107], v12, s[42:43] offset:80
	global_load_dwordx4 v[96:99], v12, s[42:43] offset:128
	global_load_dwordx4 v[92:95], v12, s[42:43] offset:144
	global_load_dwordx4 v[88:91], v12, s[42:43] offset:192
	global_load_dwordx4 v[84:87], v12, s[42:43] offset:208
	global_load_dwordx4 v[80:83], v12, s[42:43] offset:256
	global_load_dwordx4 v[76:79], v12, s[42:43] offset:272
	global_load_dwordx4 v[72:75], v12, s[42:43] offset:320
	global_load_dwordx4 v[68:71], v12, s[42:43] offset:336
	global_load_dwordx4 v[64:67], v12, s[42:43] offset:384
	global_load_dwordx4 v[60:63], v12, s[42:43] offset:400
	global_load_dwordx4 v[8:11], v12, s[42:43] offset:448
	global_load_dwordx4 v[4:7], v12, s[42:43] offset:464
	global_load_dwordx4 v[56:59], v12, s[42:43] offset:512
	global_load_dwordx4 v[52:55], v12, s[42:43] offset:528
	global_load_dwordx4 v[48:51], v12, s[42:43] offset:576
	global_load_dwordx4 v[44:47], v12, s[42:43] offset:592
	global_load_dwordx4 v[40:43], v12, s[42:43] offset:640
	global_load_dwordx4 v[36:39], v12, s[42:43] offset:656
	global_load_dwordx4 v[24:27], v12, s[42:43] offset:704
	global_load_dwordx4 v[20:23], v12, s[42:43] offset:720
	v_lshl_add_u64 v[124:125], s[12:13], 0, v[12:13]
	v_lshl_add_u64 v[170:171], s[14:15], 0, v[12:13]
	v_ashrrev_i32_e32 v12, 2, v126
	v_and_b32_e32 v12, -16, v12
	v_ashrrev_i32_e32 v13, 31, v12
	v_lshlrev_b32_e32 v126, 6, v126
	v_lshlrev_b64 v[16:17], 2, v[12:13]
	v_and_b32_e32 v178, 0xfc0, v126
	v_mov_b32_e32 v179, v3
	v_lshl_add_u64 v[18:19], v[124:125], 0, v[16:17]
	v_lshl_add_u64 v[180:181], v[124:125], 0, v[178:179]
	v_lshl_add_u64 v[32:33], v[170:171], 0, v[16:17]
	global_load_dwordx4 v[12:15], v[18:19], off offset:16
	global_load_dwordx4 v[28:31], v[18:19], off
	s_nop 0
	global_load_dwordx4 v[16:19], v[32:33], off offset:16
	s_nop 0
	global_load_dwordx4 v[32:35], v[32:33], off
	s_lshl_b32 s18, s5, 12
	v_and_b32_e32 v202, 63, v201
	s_add_i32 s18, s18, 0
	s_add_i32 s18, s18, 0x14800
	v_lshlrev_b32_e32 v203, 4, v202
	v_add_u32_e32 v200, s18, v203
	s_lshl_b32 s5, s5, 10
	s_add_i32 s29, s5, 0
	s_movk_i32 s5, 0x600
	s_add_i32 m0, s29, 0x8000
	s_mov_b64 s[18:19], 0x800
	s_add_i32 s30, s29, 0x10000
	s_and_b32 s4, s4, 0x3fffffc0
	s_lshl_b32 s4, s4, 2
	s_add_i32 s4, s4, 0
	s_add_i32 s4, s4, 0x14000
	s_waitcnt vmcnt(35)
	v_lshlrev_b32_e32 v232, 16, v118
	s_waitcnt vmcnt(34)
	v_lshlrev_b32_e32 v224, 16, v122
	s_waitcnt vmcnt(33)
	v_lshlrev_b32_e32 v216, 16, v222
	v_lshlrev_b32_e32 v126, 16, v131
	v_and_b32_e32 v127, 0xffff0000, v131
	v_lshlrev_b32_e32 v124, 16, v143
	v_and_b32_e32 v125, 0xffff0000, v143
	v_lshlrev_b32_e32 v136, 16, v130
	v_and_b32_e32 v137, 0xffff0000, v130
	v_lshlrev_b32_e32 v134, 16, v142
	v_and_b32_e32 v135, 0xffff0000, v142
	v_lshlrev_b32_e32 v144, 16, v129
	v_and_b32_e32 v145, 0xffff0000, v129
	v_lshlrev_b32_e32 v138, 16, v141
	v_and_b32_e32 v139, 0xffff0000, v141
	v_lshlrev_b32_e32 v150, 16, v128
	v_and_b32_e32 v151, 0xffff0000, v128
	v_lshlrev_b32_e32 v146, 16, v140
	v_and_b32_e32 v147, 0xffff0000, v140
	v_lshlrev_b32_e32 v154, 16, v167
	v_and_b32_e32 v155, 0xffff0000, v167
	v_lshlrev_b32_e32 v152, 16, v175
	v_and_b32_e32 v153, 0xffff0000, v175
	v_lshlrev_b32_e32 v158, 16, v166
	v_and_b32_e32 v159, 0xffff0000, v166
	v_lshlrev_b32_e32 v156, 16, v174
	v_and_b32_e32 v157, 0xffff0000, v174
	v_lshlrev_b32_e32 v162, 16, v165
	v_and_b32_e32 v163, 0xffff0000, v165
	v_lshlrev_b32_e32 v160, 16, v173
	v_and_b32_e32 v161, 0xffff0000, v173
	v_lshlrev_b32_e32 v166, 16, v164
	v_and_b32_e32 v167, 0xffff0000, v164
	v_lshlrev_b32_e32 v164, 16, v172
	v_and_b32_e32 v165, 0xffff0000, v172
	s_waitcnt vmcnt(31)
	v_lshlrev_b32_e32 v128, 16, v185
	v_and_b32_e32 v129, 0xffff0000, v185
	v_lshlrev_b32_e32 v130, 16, v183
	v_and_b32_e32 v131, 0xffff0000, v183
	v_lshlrev_b32_e32 v140, 16, v184
	v_and_b32_e32 v141, 0xffff0000, v184
	v_lshlrev_b32_e32 v142, 16, v182
	v_and_b32_e32 v143, 0xffff0000, v182
	s_waitcnt vmcnt(30)
	v_lshlrev_b32_e32 v168, 16, v189
	v_and_b32_e32 v169, 0xffff0000, v189
	v_lshlrev_b32_e32 v172, 16, v187
	v_and_b32_e32 v173, 0xffff0000, v187
	v_lshlrev_b32_e32 v174, 16, v188
	v_and_b32_e32 v175, 0xffff0000, v188
	v_lshlrev_b32_e32 v176, 16, v186
	v_and_b32_e32 v177, 0xffff0000, v186
	s_waitcnt vmcnt(28)
	v_lshlrev_b32_e32 v182, 16, v193
	v_and_b32_e32 v183, 0xffff0000, v193
	v_lshlrev_b32_e32 v184, 16, v191
	v_and_b32_e32 v185, 0xffff0000, v191
	v_lshlrev_b32_e32 v186, 16, v192
	v_and_b32_e32 v187, 0xffff0000, v192
	v_lshlrev_b32_e32 v188, 16, v190
	v_and_b32_e32 v189, 0xffff0000, v190
	v_lshlrev_b32_e32 v190, 16, v207
	v_and_b32_e32 v191, 0xffff0000, v207
	v_lshlrev_b32_e32 v192, 16, v205
	v_and_b32_e32 v193, 0xffff0000, v205
	v_lshlrev_b32_e32 v194, 16, v206
	v_and_b32_e32 v195, 0xffff0000, v206
	v_lshlrev_b32_e32 v196, 16, v204
	v_and_b32_e32 v197, 0xffff0000, v204
	v_lshlrev_b32_e32 v204, 16, v215
	v_and_b32_e32 v205, 0xffff0000, v215
	v_lshlrev_b32_e32 v206, 16, v213
	v_and_b32_e32 v207, 0xffff0000, v213
	v_lshlrev_b32_e32 v208, 16, v214
	v_and_b32_e32 v209, 0xffff0000, v214
	v_lshlrev_b32_e32 v210, 16, v212
	v_and_b32_e32 v211, 0xffff0000, v212
	v_lshlrev_b32_e32 v212, 16, v223
	v_and_b32_e32 v213, 0xffff0000, v223
	v_lshlrev_b32_e32 v214, 16, v221
	v_and_b32_e32 v215, 0xffff0000, v221
	v_and_b32_e32 v217, 0xffff0000, v222
	v_lshlrev_b32_e32 v218, 16, v220
	v_and_b32_e32 v219, 0xffff0000, v220
	v_lshlrev_b32_e32 v220, 16, v123
	v_and_b32_e32 v221, 0xffff0000, v123
	v_lshlrev_b32_e32 v222, 16, v121
	v_and_b32_e32 v223, 0xffff0000, v121
	v_and_b32_e32 v225, 0xffff0000, v122
	v_lshlrev_b32_e32 v122, 16, v120
	v_and_b32_e32 v123, 0xffff0000, v120
	v_lshlrev_b32_e32 v120, 16, v119
	v_and_b32_e32 v121, 0xffff0000, v119
	v_and_b32_e32 v119, 0xffff0000, v116
	v_and_b32_e32 v233, 0xffff0000, v118
	v_lshlrev_b32_e32 v118, 16, v116
	v_mul_f32_e32 v116, v119, v119
	v_lshlrev_b32_e32 v230, 16, v117
	v_and_b32_e32 v231, 0xffff0000, v117
	v_pk_fma_f32 v[116:117], v[118:119], v[118:119], v[116:117] op_sel_hi:[1,1,0]
	v_mul_f32_e32 v226, v231, v231
	v_pk_fma_f32 v[116:117], v[230:231], v[230:231], v[116:117]
	s_nop 0
	v_pk_add_f32 v[116:117], v[226:227], v[116:117] op_sel_hi:[0,1]
	v_pk_fma_f32 v[116:117], v[232:233], v[232:233], v[116:117]
	v_mul_f32_e32 v226, v233, v233
	v_pk_add_f32 v[116:117], v[226:227], v[116:117] op_sel_hi:[0,1]
	v_pk_fma_f32 v[116:117], v[120:121], v[120:121], v[116:117]
	v_mul_f32_e32 v226, v121, v121
	v_pk_add_f32 v[116:117], v[226:227], v[116:117] op_sel_hi:[0,1]
	v_pk_fma_f32 v[116:117], v[122:123], v[122:123], v[116:117]
	v_mul_f32_e32 v226, v123, v123
	v_pk_add_f32 v[116:117], v[226:227], v[116:117] op_sel_hi:[0,1]
	v_pk_fma_f32 v[116:117], v[222:223], v[222:223], v[116:117]
	v_mul_f32_e32 v226, v223, v223
	v_pk_add_f32 v[116:117], v[226:227], v[116:117] op_sel_hi:[0,1]
	v_pk_fma_f32 v[116:117], v[224:225], v[224:225], v[116:117]
	v_mul_f32_e32 v226, v225, v225
	v_pk_add_f32 v[116:117], v[226:227], v[116:117] op_sel_hi:[0,1]
	v_pk_fma_f32 v[116:117], v[220:221], v[220:221], v[116:117]
	v_mul_f32_e32 v226, v221, v221
	v_pk_add_f32 v[116:117], v[226:227], v[116:117] op_sel_hi:[0,1]
	v_pk_fma_f32 v[116:117], v[218:219], v[218:219], v[116:117]
	v_mul_f32_e32 v226, v219, v219
	v_pk_add_f32 v[116:117], v[226:227], v[116:117] op_sel_hi:[0,1]
	v_pk_fma_f32 v[116:117], v[214:215], v[214:215], v[116:117]
	v_mul_f32_e32 v226, v215, v215
	v_pk_add_f32 v[116:117], v[226:227], v[116:117] op_sel_hi:[0,1]
	v_pk_fma_f32 v[116:117], v[216:217], v[216:217], v[116:117]
	v_mul_f32_e32 v226, v217, v217
	v_pk_add_f32 v[116:117], v[226:227], v[116:117] op_sel_hi:[0,1]
	v_pk_fma_f32 v[116:117], v[212:213], v[212:213], v[116:117]
	v_mul_f32_e32 v226, v213, v213
	v_pk_add_f32 v[116:117], v[226:227], v[116:117] op_sel_hi:[0,1]
	v_pk_fma_f32 v[116:117], v[210:211], v[210:211], v[116:117]
	v_mul_f32_e32 v226, v211, v211
	v_pk_add_f32 v[116:117], v[226:227], v[116:117] op_sel_hi:[0,1]
	v_pk_fma_f32 v[116:117], v[206:207], v[206:207], v[116:117]
	v_mul_f32_e32 v226, v207, v207
	v_pk_add_f32 v[116:117], v[226:227], v[116:117] op_sel_hi:[0,1]
	v_pk_fma_f32 v[116:117], v[208:209], v[208:209], v[116:117]
	v_mul_f32_e32 v226, v209, v209
	v_pk_add_f32 v[116:117], v[226:227], v[116:117] op_sel_hi:[0,1]
	v_pk_fma_f32 v[116:117], v[204:205], v[204:205], v[116:117]
	v_mul_f32_e32 v226, v205, v205
	v_pk_add_f32 v[116:117], v[226:227], v[116:117] op_sel_hi:[0,1]
	v_pk_fma_f32 v[116:117], v[196:197], v[196:197], v[116:117]
	v_mul_f32_e32 v226, v197, v197
	v_pk_add_f32 v[116:117], v[226:227], v[116:117] op_sel_hi:[0,1]
	v_pk_fma_f32 v[116:117], v[192:193], v[192:193], v[116:117]
	v_mul_f32_e32 v226, v193, v193
	v_pk_add_f32 v[116:117], v[226:227], v[116:117] op_sel_hi:[0,1]
	v_pk_fma_f32 v[116:117], v[194:195], v[194:195], v[116:117]
	v_mul_f32_e32 v226, v195, v195
	v_pk_add_f32 v[116:117], v[226:227], v[116:117] op_sel_hi:[0,1]
	v_pk_fma_f32 v[116:117], v[190:191], v[190:191], v[116:117]
	v_mul_f32_e32 v226, v191, v191
	v_pk_add_f32 v[116:117], v[226:227], v[116:117] op_sel_hi:[0,1]
	v_pk_fma_f32 v[116:117], v[188:189], v[188:189], v[116:117]
	v_mul_f32_e32 v226, v189, v189
	v_pk_add_f32 v[116:117], v[226:227], v[116:117] op_sel_hi:[0,1]
	v_pk_fma_f32 v[116:117], v[184:185], v[184:185], v[116:117]
	v_mul_f32_e32 v226, v185, v185
	v_pk_add_f32 v[116:117], v[226:227], v[116:117] op_sel_hi:[0,1]
	v_pk_fma_f32 v[116:117], v[186:187], v[186:187], v[116:117]
	v_mul_f32_e32 v226, v187, v187
	v_pk_add_f32 v[116:117], v[226:227], v[116:117] op_sel_hi:[0,1]
	v_pk_fma_f32 v[116:117], v[182:183], v[182:183], v[116:117]
	v_mul_f32_e32 v226, v183, v183
	v_pk_add_f32 v[116:117], v[226:227], v[116:117] op_sel_hi:[0,1]
	v_pk_fma_f32 v[116:117], v[176:177], v[176:177], v[116:117]
	v_mul_f32_e32 v226, v177, v177
	v_pk_add_f32 v[116:117], v[226:227], v[116:117] op_sel_hi:[0,1]
	v_pk_fma_f32 v[116:117], v[172:173], v[172:173], v[116:117]
	v_mul_f32_e32 v226, v173, v173
	v_pk_add_f32 v[116:117], v[226:227], v[116:117] op_sel_hi:[0,1]
	v_pk_fma_f32 v[116:117], v[174:175], v[174:175], v[116:117]
	v_mul_f32_e32 v226, v175, v175
	v_pk_add_f32 v[116:117], v[226:227], v[116:117] op_sel_hi:[0,1]
	v_pk_fma_f32 v[116:117], v[168:169], v[168:169], v[116:117]
	v_mul_f32_e32 v226, v169, v169
	v_pk_add_f32 v[116:117], v[226:227], v[116:117] op_sel_hi:[0,1]
	v_pk_fma_f32 v[116:117], v[142:143], v[142:143], v[116:117]
	v_mul_f32_e32 v226, v143, v143
	v_pk_add_f32 v[116:117], v[226:227], v[116:117] op_sel_hi:[0,1]
	v_pk_fma_f32 v[116:117], v[130:131], v[130:131], v[116:117]
	v_mul_f32_e32 v226, v131, v131
	v_pk_add_f32 v[116:117], v[226:227], v[116:117] op_sel_hi:[0,1]
	v_pk_fma_f32 v[116:117], v[140:141], v[140:141], v[116:117]
	v_mul_f32_e32 v226, v141, v141
	v_pk_add_f32 v[116:117], v[226:227], v[116:117] op_sel_hi:[0,1]
	v_pk_fma_f32 v[116:117], v[128:129], v[128:129], v[116:117]
	v_mul_f32_e32 v226, v129, v129
	v_pk_add_f32 v[116:117], v[226:227], v[116:117] op_sel_hi:[0,1]
	v_pk_fma_f32 v[116:117], v[166:167], v[166:167], v[116:117]
	v_mul_f32_e32 v226, v167, v167
	v_pk_add_f32 v[116:117], v[226:227], v[116:117] op_sel_hi:[0,1]
	v_pk_fma_f32 v[116:117], v[162:163], v[162:163], v[116:117]
	v_mul_f32_e32 v226, v163, v163
	v_pk_add_f32 v[116:117], v[226:227], v[116:117] op_sel_hi:[0,1]
	v_pk_fma_f32 v[116:117], v[158:159], v[158:159], v[116:117]
	v_mul_f32_e32 v226, v159, v159
	v_pk_add_f32 v[116:117], v[226:227], v[116:117] op_sel_hi:[0,1]
	v_pk_fma_f32 v[116:117], v[154:155], v[154:155], v[116:117]
	v_mul_f32_e32 v226, v155, v155
	v_pk_add_f32 v[116:117], v[226:227], v[116:117] op_sel_hi:[0,1]
	v_pk_fma_f32 v[116:117], v[164:165], v[164:165], v[116:117]
	v_mul_f32_e32 v226, v165, v165
	v_pk_add_f32 v[116:117], v[226:227], v[116:117] op_sel_hi:[0,1]
	v_pk_fma_f32 v[116:117], v[160:161], v[160:161], v[116:117]
	v_mul_f32_e32 v226, v161, v161
	v_pk_add_f32 v[116:117], v[226:227], v[116:117] op_sel_hi:[0,1]
	v_pk_fma_f32 v[116:117], v[156:157], v[156:157], v[116:117]
	v_mul_f32_e32 v226, v157, v157
	v_pk_add_f32 v[116:117], v[226:227], v[116:117] op_sel_hi:[0,1]
	v_pk_fma_f32 v[116:117], v[152:153], v[152:153], v[116:117]
	v_mul_f32_e32 v226, v153, v153
	v_pk_add_f32 v[116:117], v[226:227], v[116:117] op_sel_hi:[0,1]
	v_pk_fma_f32 v[116:117], v[150:151], v[150:151], v[116:117]
	v_mul_f32_e32 v226, v151, v151
	v_pk_add_f32 v[116:117], v[226:227], v[116:117] op_sel_hi:[0,1]
	v_pk_fma_f32 v[116:117], v[144:145], v[144:145], v[116:117]
	v_mul_f32_e32 v226, v145, v145
	v_pk_add_f32 v[116:117], v[226:227], v[116:117] op_sel_hi:[0,1]
	v_pk_fma_f32 v[116:117], v[136:137], v[136:137], v[116:117]
	v_mul_f32_e32 v226, v137, v137
	v_pk_add_f32 v[116:117], v[226:227], v[116:117] op_sel_hi:[0,1]
	v_pk_fma_f32 v[116:117], v[126:127], v[126:127], v[116:117]
	v_mul_f32_e32 v226, v127, v127
	v_pk_add_f32 v[116:117], v[226:227], v[116:117] op_sel_hi:[0,1]
	v_pk_fma_f32 v[116:117], v[146:147], v[146:147], v[116:117]
	v_mul_f32_e32 v226, v147, v147
	v_pk_add_f32 v[116:117], v[226:227], v[116:117] op_sel_hi:[0,1]
	v_pk_fma_f32 v[116:117], v[138:139], v[138:139], v[116:117]
	v_mul_f32_e32 v226, v139, v139
	v_pk_add_f32 v[116:117], v[226:227], v[116:117] op_sel_hi:[0,1]
	v_pk_fma_f32 v[116:117], v[134:135], v[134:135], v[116:117]
	v_mul_f32_e32 v226, v135, v135
	v_pk_add_f32 v[116:117], v[226:227], v[116:117] op_sel_hi:[0,1]
	v_pk_fma_f32 v[116:117], v[124:125], v[124:125], v[116:117]
	v_mul_f32_e32 v226, v125, v125
	v_pk_add_f32 v[116:117], v[226:227], v[116:117] op_sel_hi:[0,1]
	v_mov_b32_e32 v117, v116
	s_nop 1
	v_permlane32_swap_b32_e32 v116, v117
	v_add_f32_e32 v116, v116, v117
	v_fmamk_f32 v116, v116, 0x3baaaaab, v198
	v_mul_f32_e32 v117, 0x4b800000, v116
	v_cmp_gt_f32_e32 vcc, s38, v116
	s_nop 1
	v_cndmask_b32_e32 v116, v116, v117, vcc
	v_rsq_f32_e32 v234, v116
	v_lshl_add_u64 v[116:117], v[170:171], 0, v[178:179]
	global_load_dwordx4 v[226:229], v[180:181], off offset:16
	s_nop 0
	global_load_dwordx4 v[178:181], v[180:181], off
	v_mul_f32_e32 v170, 0x45800000, v234
	v_cndmask_b32_e32 v170, v234, v170, vcc
	v_pk_mul_f32 v[118:119], v[170:171], v[118:119] op_sel_hi:[0,1]
	s_waitcnt vmcnt(29)
	v_pk_mul_f32 v[112:113], v[112:113], v[118:119]
	v_pk_mul_f32 v[118:119], v[170:171], v[230:231] op_sel_hi:[0,1]
	v_pk_mul_f32 v[114:115], v[114:115], v[118:119]
	v_pk_mul_f32 v[118:119], v[170:171], v[232:233] op_sel_hi:[0,1]
	global_load_dwordx4 v[230:233], v[116:117], off offset:16
	global_load_dwordx4 v[240:243], v[116:117], off
	s_waitcnt vmcnt(30)
	v_pk_mul_f32 v[118:119], v[100:101], v[118:119]
	v_pk_mul_f32 v[100:101], v[170:171], v[120:121] op_sel_hi:[0,1]
	v_pk_mul_f32 v[120:121], v[102:103], v[100:101]
	v_cvt_pk_bf16_f32 v100, v112, v113
	v_pk_mul_f32 v[112:113], v[170:171], v[122:123] op_sel_hi:[0,1]
	s_waitcnt vmcnt(29)
	v_pk_mul_f32 v[108:109], v[108:109], v[112:113]
	v_pk_mul_f32 v[112:113], v[170:171], v[224:225] op_sel_hi:[0,1]
	s_waitcnt vmcnt(28)
	v_pk_mul_f32 v[112:113], v[104:105], v[112:113]
	v_pk_mul_f32 v[104:105], v[170:171], v[222:223] op_sel_hi:[0,1]
	v_pk_mul_f32 v[110:111], v[110:111], v[104:105]
	v_pk_mul_f32 v[104:105], v[170:171], v[220:221] op_sel_hi:[0,1]
	v_cvt_pk_bf16_f32 v101, v114, v115
	v_pk_mul_f32 v[114:115], v[106:107], v[104:105]
	v_cvt_pk_bf16_f32 v104, v108, v109
	v_pk_mul_f32 v[108:109], v[170:171], v[218:219] op_sel_hi:[0,1]
	s_waitcnt vmcnt(27)
	v_pk_mul_f32 v[96:97], v[96:97], v[108:109]
	v_pk_mul_f32 v[108:109], v[170:171], v[216:217] op_sel_hi:[0,1]
	s_waitcnt vmcnt(26)
	v_pk_mul_f32 v[92:93], v[92:93], v[108:109]
	v_cvt_pk_bf16_f32 v105, v110, v111
	v_cvt_pk_bf16_f32 v110, v92, v93
	v_pk_mul_f32 v[92:93], v[170:171], v[210:211] op_sel_hi:[0,1]
	s_waitcnt vmcnt(25)
	v_pk_mul_f32 v[88:89], v[88:89], v[92:93]
	v_pk_mul_f32 v[92:93], v[170:171], v[208:209] op_sel_hi:[0,1]
	s_waitcnt vmcnt(24)
	v_pk_mul_f32 v[84:85], v[84:85], v[92:93]
	v_cvt_pk_bf16_f32 v107, v114, v115
	v_cvt_pk_bf16_f32 v114, v84, v85
	v_pk_mul_f32 v[84:85], v[170:171], v[196:197] op_sel_hi:[0,1]
	s_waitcnt vmcnt(23)
	v_pk_mul_f32 v[80:81], v[80:81], v[84:85]
	v_pk_mul_f32 v[84:85], v[170:171], v[194:195] op_sel_hi:[0,1]
	s_waitcnt vmcnt(22)
	v_pk_mul_f32 v[76:77], v[76:77], v[84:85]
	v_cvt_pk_bf16_f32 v102, v118, v119
	v_cvt_pk_bf16_f32 v118, v76, v77
	v_pk_mul_f32 v[76:77], v[170:171], v[188:189] op_sel_hi:[0,1]
	s_waitcnt vmcnt(21)
	v_pk_mul_f32 v[72:73], v[76:77], v[72:73]
	v_pk_mul_f32 v[76:77], v[170:171], v[186:187] op_sel_hi:[0,1]
	s_waitcnt vmcnt(20)
	v_pk_mul_f32 v[68:69], v[76:77], v[68:69]
	v_pk_mul_f32 v[108:109], v[170:171], v[214:215] op_sel_hi:[0,1]
	v_cvt_pk_bf16_f32 v122, v68, v69
	v_pk_mul_f32 v[68:69], v[170:171], v[176:177] op_sel_hi:[0,1]
	s_waitcnt vmcnt(19)
	v_pk_mul_f32 v[64:65], v[68:69], v[64:65]
	v_pk_mul_f32 v[68:69], v[170:171], v[174:175] op_sel_hi:[0,1]
	s_waitcnt vmcnt(18)
	v_pk_mul_f32 v[60:61], v[68:69], v[60:61]
	v_pk_mul_f32 v[68:69], v[170:171], v[172:173] op_sel_hi:[0,1]
	v_pk_mul_f32 v[66:67], v[68:69], v[66:67]
	v_pk_mul_f32 v[68:69], v[170:171], v[168:169] op_sel_hi:[0,1]
	v_pk_mul_f32 v[62:63], v[68:69], v[62:63]
	v_pk_mul_f32 v[68:69], v[170:171], v[166:167] op_sel_hi:[0,1]
	s_waitcnt vmcnt(15)
	v_pk_mul_f32 v[56:57], v[68:69], v[56:57]
	v_pk_mul_f32 v[68:69], v[170:171], v[158:159] op_sel_hi:[0,1]
	s_waitcnt vmcnt(14)
	v_pk_mul_f32 v[52:53], v[68:69], v[52:53]
	v_pk_mul_f32 v[68:69], v[170:171], v[162:163] op_sel_hi:[0,1]
	v_pk_mul_f32 v[58:59], v[68:69], v[58:59]
	v_pk_mul_f32 v[68:69], v[170:171], v[154:155] op_sel_hi:[0,1]
	v_pk_mul_f32 v[54:55], v[68:69], v[54:55]
	v_pk_mul_f32 v[68:69], v[170:171], v[164:165] op_sel_hi:[0,1]
	s_waitcnt vmcnt(13)
	v_pk_mul_f32 v[48:49], v[68:69], v[48:49]
	v_pk_mul_f32 v[68:69], v[170:171], v[156:157] op_sel_hi:[0,1]
	s_waitcnt vmcnt(12)
	v_pk_mul_f32 v[44:45], v[68:69], v[44:45]
	v_pk_mul_f32 v[68:69], v[170:171], v[160:161] op_sel_hi:[0,1]
	v_pk_mul_f32 v[50:51], v[68:69], v[50:51]
	v_pk_mul_f32 v[68:69], v[170:171], v[152:153] op_sel_hi:[0,1]
	v_pk_mul_f32 v[46:47], v[68:69], v[46:47]
	v_pk_mul_f32 v[68:69], v[170:171], v[150:151] op_sel_hi:[0,1]
	s_waitcnt vmcnt(11)
	v_pk_mul_f32 v[40:41], v[68:69], v[40:41]
	v_pk_mul_f32 v[68:69], v[170:171], v[136:137] op_sel_hi:[0,1]
	s_waitcnt vmcnt(10)
	v_pk_mul_f32 v[36:37], v[68:69], v[36:37]
	v_pk_mul_f32 v[68:69], v[170:171], v[144:145] op_sel_hi:[0,1]
	v_pk_mul_f32 v[42:43], v[68:69], v[42:43]
	v_pk_mul_f32 v[68:69], v[170:171], v[126:127] op_sel_hi:[0,1]
	v_pk_mul_f32 v[38:39], v[68:69], v[38:39]
	v_pk_mul_f32 v[68:69], v[170:171], v[146:147] op_sel_hi:[0,1]
	s_waitcnt vmcnt(9)
	v_pk_mul_f32 v[24:25], v[68:69], v[24:25]
	v_pk_mul_f32 v[68:69], v[170:171], v[134:135] op_sel_hi:[0,1]
	s_waitcnt vmcnt(8)
	v_pk_mul_f32 v[20:21], v[68:69], v[20:21]
	v_pk_mul_f32 v[68:69], v[170:171], v[138:139] op_sel_hi:[0,1]
	v_pk_mul_f32 v[26:27], v[68:69], v[26:27]
	v_pk_mul_f32 v[68:69], v[170:171], v[124:125] op_sel_hi:[0,1]
	v_pk_mul_f32 v[22:23], v[68:69], v[22:23]
	s_waitcnt vmcnt(4)
	v_pk_mul_f32 v[68:69], v[56:57], v[32:33]
	v_pk_mul_f32 v[32:33], v[48:49], v[32:33]
	v_pk_fma_f32 v[68:69], v[48:49], v[28:29], v[68:69]
	v_pk_fma_f32 v[28:29], v[56:57], v[28:29], v[32:33] neg_lo:[0,0,1] neg_hi:[0,0,1]
	v_pk_mul_f32 v[32:33], v[58:59], v[34:35]
	v_pk_mul_f32 v[34:35], v[50:51], v[34:35]
	v_pk_fma_f32 v[32:33], v[50:51], v[30:31], v[32:33]
	v_pk_fma_f32 v[30:31], v[58:59], v[30:31], v[34:35] neg_lo:[0,0,1] neg_hi:[0,0,1]
	v_pk_mul_f32 v[34:35], v[52:53], v[16:17]
	v_pk_mul_f32 v[16:17], v[44:45], v[16:17]
	v_pk_fma_f32 v[34:35], v[44:45], v[12:13], v[34:35]
	v_pk_fma_f32 v[16:17], v[52:53], v[12:13], v[16:17] neg_lo:[0,0,1] neg_hi:[0,0,1]
	v_pk_mul_f32 v[12:13], v[54:55], v[18:19]
	v_pk_mul_f32 v[92:93], v[170:171], v[206:207] op_sel_hi:[0,1]
	v_pk_fma_f32 v[44:45], v[46:47], v[14:15], v[12:13]
	v_pk_mul_f32 v[12:13], v[46:47], v[18:19]
	v_pk_mul_f32 v[84:85], v[170:171], v[192:193] op_sel_hi:[0,1]
	v_pk_fma_f32 v[18:19], v[54:55], v[14:15], v[12:13] neg_lo:[0,0,1] neg_hi:[0,0,1]
	s_waitcnt vmcnt(0)
	v_pk_mul_f32 v[12:13], v[40:41], v[240:241]
	v_cvt_pk_bf16_f32 v14, v16, v17
	v_pk_fma_f32 v[46:47], v[24:25], v[178:179], v[12:13]
	v_pk_mul_f32 v[12:13], v[24:25], v[240:241]
	v_cvt_pk_bf16_f32 v15, v18, v19
	v_pk_fma_f32 v[24:25], v[40:41], v[178:179], v[12:13] neg_lo:[0,0,1] neg_hi:[0,0,1]
	v_pk_mul_f32 v[12:13], v[42:43], v[242:243]
	v_lshlrev_b32_e32 v19, 3, v201
	v_pk_fma_f32 v[40:41], v[26:27], v[180:181], v[12:13]
	v_pk_mul_f32 v[12:13], v[26:27], v[242:243]
	v_pk_mul_f32 v[76:77], v[170:171], v[184:185] op_sel_hi:[0,1]
	v_pk_fma_f32 v[26:27], v[42:43], v[180:181], v[12:13] neg_lo:[0,0,1] neg_hi:[0,0,1]
	v_pk_mul_f32 v[12:13], v[36:37], v[230:231]
	v_add_u32_e32 v154, s4, v2
	v_pk_fma_f32 v[42:43], v[20:21], v[226:227], v[12:13]
	v_pk_mul_f32 v[12:13], v[20:21], v[230:231]
	v_pk_mul_f32 v[98:99], v[98:99], v[108:109]
	v_pk_fma_f32 v[20:21], v[36:37], v[226:227], v[12:13] neg_lo:[0,0,1] neg_hi:[0,0,1]
	v_pk_mul_f32 v[12:13], v[38:39], v[232:233]
	v_pk_mul_f32 v[108:109], v[170:171], v[212:213] op_sel_hi:[0,1]
	v_pk_fma_f32 v[36:37], v[22:23], v[228:229], v[12:13]
	v_pk_mul_f32 v[12:13], v[22:23], v[232:233]
	v_pk_mul_f32 v[90:91], v[90:91], v[92:93]
	v_pk_fma_f32 v[22:23], v[38:39], v[228:229], v[12:13] neg_lo:[0,0,1] neg_hi:[0,0,1]
	v_cvt_pk_bf16_f32 v12, v28, v29
	v_cvt_pk_bf16_f32 v13, v30, v31
	ds_write_b128 v200, v[12:15]
	v_cvt_pk_bf16_f32 v12, v68, v69
	v_cvt_pk_bf16_f32 v13, v32, v33
	v_cvt_pk_bf16_f32 v14, v34, v35
	v_cvt_pk_bf16_f32 v15, v44, v45
	ds_write_b128 v200, v[12:15] offset:1024
	v_cvt_pk_bf16_f32 v12, v24, v25
	v_cvt_pk_bf16_f32 v13, v26, v27
	v_cvt_pk_bf16_f32 v14, v20, v21
	v_cvt_pk_bf16_f32 v15, v22, v23
	ds_write_b128 v200, v[12:15] offset:2048
	v_cvt_pk_bf16_f32 v12, v46, v47
	v_cvt_pk_bf16_f32 v13, v40, v41
	v_cvt_pk_bf16_f32 v14, v42, v43
	v_cvt_pk_bf16_f32 v15, v36, v37
	ds_write_b128 v200, v[12:15] offset:3072
	v_bfe_u32 v12, v201, 2, 2
	v_lshrrev_b32_e32 v14, 1, v201
	v_ashrrev_i32_e32 v15, 4, v201
	v_and_or_b32 v14, v14, 8, v12
	v_and_b32_e32 v12, 0x60, v201
	v_lshrrev_b32_e32 v16, 1, v15
	v_and_or_b32 v18, v19, 24, v12
	v_and_b32_e32 v12, -16, v15
	v_and_b32_e32 v16, 4, v16
	v_or3_b32 v12, v16, v12, v14
	v_add_u32_e32 v16, 0x200, v201
	v_ashrrev_i32_e32 v24, 4, v16
	v_and_b32_e32 v13, 15, v201
	v_lshrrev_b32_e32 v16, 1, v24
	v_bitop3_b32 v21, v15, v13, 7 bitop3:0x6c
	v_bitop3_b32 v26, v24, v13, 7 bitop3:0x6c
	v_and_b32_e32 v13, -16, v24
	v_and_b32_e32 v16, 4, v16
	v_ashrrev_i32_e32 v27, 3, v201
	v_mul_i32_i24_sdwa v134, sext(v15), s5 dst_sel:DWORD dst_unused:UNUSED_PAD src0_sel:WORD_0 src1_sel:DWORD
	v_or3_b32 v14, v16, v13, v14
	v_xor_b32_e32 v13, v27, v201
	v_ashrrev_i32_e32 v135, 31, v134
	v_lshlrev_b32_e32 v13, 3, v13
	v_lshl_add_u64 v[16:17], v[134:135], 1, s[16:17]
	v_lshlrev_b32_e32 v22, 4, v21
	v_mov_b32_e32 v23, v3
	v_and_b32_e32 v20, 56, v13
	v_lshl_add_u64 v[16:17], v[16:17], 0, v[22:23]
	v_ashrrev_i32_e32 v13, 31, v12
	global_load_lds_dwordx4 v[16:17], off
	v_lshlrev_b64 v[16:17], 12, v[12:13]
	v_lshl_add_u64 v[16:17], s[0:1], 0, v[16:17]
	v_lshlrev_b32_e32 v22, 1, v18
	v_lshl_add_u64 v[16:17], v[16:17], 0, v[22:23]
	v_mul_i32_i24_sdwa v136, sext(v24), s5 dst_sel:DWORD dst_unused:UNUSED_PAD src0_sel:WORD_0 src1_sel:DWORD
	v_lshl_add_u64 v[16:17], v[16:17], 0, s[18:19]
	s_mov_b32 m0, s29
	v_ashrrev_i32_e32 v137, 31, v136
	global_load_lds_dwordx4 v[16:17], off
	v_lshl_add_u64 v[16:17], v[136:137], 1, s[16:17]
	v_lshlrev_b32_e32 v24, 4, v26
	v_mov_b32_e32 v25, v3
	v_lshl_add_u64 v[16:17], v[16:17], 0, v[24:25]
	s_add_i32 m0, s29, 0xa000
	v_ashrrev_i32_e32 v15, 31, v14
	global_load_lds_dwordx4 v[16:17], off
	v_lshlrev_b64 v[16:17], 12, v[14:15]
	v_lshl_add_u64 v[16:17], s[0:1], 0, v[16:17]
	v_lshl_add_u64 v[16:17], v[16:17], 0, v[22:23]
	v_mul_i32_i24_sdwa v138, sext(v27), s5 dst_sel:DWORD dst_unused:UNUSED_PAD src0_sel:WORD_0 src1_sel:DWORD
	v_lshl_add_u64 v[16:17], v[16:17], 0, s[18:19]
	s_add_i32 m0, s29, 0x2000
	v_ashrrev_i32_e32 v139, 31, v138
	global_load_lds_dwordx4 v[16:17], off
	v_lshl_add_u64 v[16:17], v[138:139], 1, s[16:17]
	v_lshlrev_b32_e32 v22, 1, v20
	v_lshl_add_u64 v[16:17], v[16:17], 0, v[22:23]
	s_mov_b64 s[0:1], 0x100
	v_lshl_add_u64 v[16:17], v[16:17], 0, s[0:1]
	s_mov_b32 m0, s30
	v_lshlrev_b32_e32 v22, 3, v21
	global_load_lds_dwordx4 v[16:17], off
	v_pk_mul_f32 v[16:17], v[170:171], v[142:143] op_sel_hi:[0,1]
	v_pk_mul_f32 v[8:9], v[16:17], v[8:9]
	v_pk_mul_f32 v[16:17], v[170:171], v[140:141] op_sel_hi:[0,1]
	v_pk_mul_f32 v[4:5], v[16:17], v[4:5]
	v_pk_mul_f32 v[16:17], v[170:171], v[130:131] op_sel_hi:[0,1]
	v_pk_mul_f32 v[10:11], v[16:17], v[10:11]
	v_pk_mul_f32 v[16:17], v[170:171], v[128:129] op_sel_hi:[0,1]
	v_pk_mul_f32 v[6:7], v[16:17], v[6:7]
	v_cvt_pk_bf16_f32 v130, v4, v5
	v_cvt_pk_bf16_f32 v131, v6, v7
	v_lshlrev_b32_e32 v4, 1, v201
	v_lshlrev_b32_e32 v6, 4, v201
	v_and_b32_e32 v4, 32, v4
	v_and_b32_e32 v7, 0x70, v6
	v_lshlrev_b32_e32 v24, 3, v26
	v_and_b32_e32 v5, 0xc0, v203
	v_bitop3_b32 v156, v2, v6, s89 bitop3:0x78
	v_bitop3_b32 v157, v2, v7, 32 bitop3:0x36
	v_bitop3_b32 v158, v2, v7, 64 bitop3:0x36
	v_bitop3_b32 v160, v2, v7, s83 bitop3:0x36
	v_bitop3_b32 v161, v2, v7, s86 bitop3:0x36
	v_bitop3_b32 v162, v2, v7, s88 bitop3:0x36
	v_bitop3_b32 v163, v2, v7, s87 bitop3:0x36
	v_bitop3_b32 v164, v2, v7, s90 bitop3:0x36
	v_and_or_b32 v2, v19, s91, v4
	v_mov_b32_e32 v16, v3
	v_mov_b32_e32 v17, v3
	v_pk_mul_f32 v[92:93], v[170:171], v[204:205] op_sel_hi:[0,1]
	v_pk_mul_f32 v[82:83], v[82:83], v[84:85]
	v_pk_mul_f32 v[84:85], v[170:171], v[190:191] op_sel_hi:[0,1]
	v_pk_mul_f32 v[74:75], v[76:77], v[74:75]
	v_pk_mul_f32 v[76:77], v[170:171], v[182:183] op_sel_hi:[0,1]
	v_cvt_pk_bf16_f32 v124, v64, v65
	v_cvt_pk_bf16_f32 v125, v66, v67
	v_cvt_pk_bf16_f32 v126, v60, v61
	v_cvt_pk_bf16_f32 v127, v62, v63
	v_cvt_pk_bf16_f32 v128, v8, v9
	v_cvt_pk_bf16_f32 v129, v10, v11
	v_lshlrev_b64 v[140:141], 11, v[12:13]
	v_lshlrev_b64 v[142:143], 11, v[14:15]
	s_waitcnt vmcnt(0)
	v_add3_u32 v166, v5, 0, v2
	v_mov_b32_e32 v2, v3
	v_mov_b32_e32 v4, v3
	v_mov_b32_e32 v5, v3
	v_mov_b32_e32 v6, v3
	v_mov_b32_e32 v7, v3
	v_mov_b32_e32 v8, v3
	v_mov_b32_e32 v9, v3
	v_mov_b32_e32 v10, v3
	v_mov_b32_e32 v11, v3
	v_mov_b32_e32 v12, v3
	v_mov_b32_e32 v13, v3
	v_mov_b32_e32 v14, v3
	v_mov_b32_e32 v15, v3
	v_lshlrev_b32_e32 v144, 1, v22
	v_lshlrev_b32_e32 v150, 1, v24
	v_lshlrev_b32_e32 v152, 1, v20
	v_mov_b64_e32 v[66:67], v[16:17]
	v_mov_b64_e32 v[50:51], v[16:17]
	v_mov_b64_e32 v[34:35], v[16:17]
	v_pk_mul_f32 v[94:95], v[94:95], v[108:109]
	v_pk_mul_f32 v[86:87], v[86:87], v[92:93]
	v_pk_mul_f32 v[78:79], v[78:79], v[84:85]
	v_pk_mul_f32 v[70:71], v[76:77], v[70:71]
	v_lshlrev_b32_e32 v146, 1, v18
	v_mov_b64_e32 v[64:65], v[14:15]
	v_mov_b64_e32 v[62:63], v[12:13]
	v_mov_b64_e32 v[60:61], v[10:11]
	v_mov_b64_e32 v[58:59], v[8:9]
	v_mov_b64_e32 v[56:57], v[6:7]
	v_mov_b64_e32 v[54:55], v[4:5]
	v_mov_b64_e32 v[52:53], v[2:3]
	v_mov_b64_e32 v[48:49], v[14:15]
	v_mov_b64_e32 v[46:47], v[12:13]
	v_mov_b64_e32 v[44:45], v[10:11]
	v_mov_b64_e32 v[42:43], v[8:9]
	v_mov_b64_e32 v[40:41], v[6:7]
	v_mov_b64_e32 v[38:39], v[4:5]
	v_mov_b64_e32 v[36:37], v[2:3]
	v_mov_b64_e32 v[32:33], v[14:15]
	v_mov_b64_e32 v[30:31], v[12:13]
	v_mov_b64_e32 v[28:29], v[10:11]
	v_mov_b64_e32 v[26:27], v[8:9]
	v_mov_b64_e32 v[24:25], v[6:7]
	v_mov_b64_e32 v[22:23], v[4:5]
	v_mov_b64_e32 v[20:21], v[2:3]
	v_mov_b64_e32 v[18:19], v[16:17]
	v_cvt_pk_bf16_f32 v103, v120, v121
	v_cvt_pk_bf16_f32 v106, v112, v113
	v_cvt_pk_bf16_f32 v108, v96, v97
	v_cvt_pk_bf16_f32 v109, v98, v99
	v_cvt_pk_bf16_f32 v111, v94, v95
	v_cvt_pk_bf16_f32 v112, v88, v89
	v_cvt_pk_bf16_f32 v113, v90, v91
	v_cvt_pk_bf16_f32 v115, v86, v87
	v_cvt_pk_bf16_f32 v116, v80, v81
	v_cvt_pk_bf16_f32 v117, v82, v83
	v_cvt_pk_bf16_f32 v119, v78, v79
	v_cvt_pk_bf16_f32 v120, v72, v73
	v_cvt_pk_bf16_f32 v121, v74, v75
	v_cvt_pk_bf16_f32 v123, v70, v71
	v_lshlrev_b32_e32 v155, 8, v149
	v_lshlrev_b32_e32 v165, 7, v149
	v_cmp_gt_u32_e64 s[0:1], 32, v202
	v_lshl_add_u32 v159, v149, 2, s4
	s_mov_b32 s19, 0
	v_mov_b32_e32 v168, 0
	v_mov_b32_e32 v167, 0xf149f2ca
	v_mov_b64_e32 v[16:17], v[14:15]
	v_mov_b64_e32 v[14:15], v[12:13]
	v_mov_b64_e32 v[12:13], v[10:11]
	v_mov_b64_e32 v[10:11], v[8:9]
	v_mov_b64_e32 v[8:9], v[6:7]
	v_mov_b64_e32 v[6:7], v[4:5]
	v_mov_b64_e32 v[4:5], v[2:3]
	s_waitcnt vmcnt(0) lgkmcnt(0)
	s_barrier
	ds_read_b128 v[186:189], v200
	ds_read_b128 v[190:193], v200 offset:1024
	ds_read_b128 v[194:197], v200 offset:2048
	ds_read_b128 v[204:207], v200 offset:3072
	s_waitcnt lgkmcnt(0)
	v_lshl_add_u32 v208, v134, 1, v144
	v_lshl_add_u32 v209, v140, 1, v146
	v_lshl_add_u32 v210, v136, 1, v150
	v_lshl_add_u32 v211, v142, 1, v146
	v_lshl_add_u32 v212, v138, 1, v152
	v_add_u32_e32 v212, 0x100, v212
	s_and_b32 s18, s19, 1
	s_cmpk_lt_u32 s19, 0x47
	s_mov_b64 s[4:5], -1
	s_cbranch_scc1 .LBB0_514
	s_branch .LBB0_513

.LBB0_514:
	s_lshl_b32 s33, s18, 14
	v_add3_u32 v224, s33, v156, v155
	v_add3_u32 v225, s33, v157, v155
	ds_read_b128 v[170:173], v224 offset:40960
	ds_read_b128 v[174:177], v225 offset:40960
	ds_read_b128 v[178:181], v225 offset:32768
	ds_read_b128 v[182:185], v224 offset:32768
	s_andn2_b64 vcc, exec, s[4:5]
	s_add_i32 s31, s19, 1
	s_cbranch_vccnz .LBB0_516
	s_sub_u32 s35, s19, 63
	s_cmp_lt_u32 s19, 63
	s_cselect_b32 s100, s31, s35
	s_cselect_b32 s5, s17, s26
	s_cselect_b32 s4, s16, s25
	s_cselect_b32 s35, s24, s28
	s_cselect_b32 s34, s23, s27
	s_mul_i32 s101, s100, 0x30000
	s_add_u32 s4, s4, s101
	s_addc_u32 s5, s5, 0
	s_lshl_b32 s101, s100, 18
	s_add_u32 s34, s34, s101
	s_addc_u32 s35, s35, 0
	s_lshl_b32 s33, s18, 14
	s_xor_b32 s100, s33, 0x4000
	s_add_i32 s100, s29, s100
	s_add_i32 m0, s100, 0x8000
	s_nop 0
	global_load_lds_dwordx4 v208, s[4:5]
	s_mov_b32 m0, s100
	s_nop 0
	global_load_lds_dwordx4 v209, s[34:35]
	s_add_i32 m0, s100, 0xa000
	s_nop 0
	global_load_lds_dwordx4 v210, s[4:5]
	s_add_i32 m0, s100, 0x2000
	s_nop 0
	global_load_lds_dwordx4 v211, s[34:35]
	s_lshl_b32 s34, s18, 13
	s_xor_b32 s101, s34, 0x2000
	s_add_i32 m0, s30, s101
	s_nop 0
	global_load_lds_dwordx4 v212, s[4:5]

	.amdhsa_kernel _Z6mk_fwd7ParamsH
		.amdhsa_group_segment_fixed_size 0
		.amdhsa_private_segment_fixed_size 0
		.amdhsa_kernarg_size 520
		.amdhsa_user_sgpr_count 2
		.amdhsa_user_sgpr_dispatch_ptr 0
		.amdhsa_user_sgpr_queue_ptr 0
		.amdhsa_user_sgpr_kernarg_segment_ptr 1
		.amdhsa_user_sgpr_dispatch_id 0
		.amdhsa_user_sgpr_kernarg_preload_length 0
		.amdhsa_user_sgpr_kernarg_preload_offset 0
		.amdhsa_user_sgpr_private_segment_size 0
		.amdhsa_uses_dynamic_stack 0
		.amdhsa_enable_private_segment 0
		.amdhsa_system_sgpr_workgroup_id_x 1
		.amdhsa_system_sgpr_workgroup_id_y 0
		.amdhsa_system_sgpr_workgroup_id_z 0
		.amdhsa_system_sgpr_workgroup_info 0
		.amdhsa_system_vgpr_workitem_id 0
		.amdhsa_next_free_vgpr 256
		.amdhsa_next_free_sgpr 102
		.amdhsa_accum_offset 256
		.amdhsa_reserve_vcc 1
		.amdhsa_float_round_mode_32 0
		.amdhsa_float_round_mode_16_64 0
		.amdhsa_float_denorm_mode_32 3
		.amdhsa_float_denorm_mode_16_64 3
		.amdhsa_dx10_clamp 1
		.amdhsa_ieee_mode 1
		.amdhsa_fp16_overflow 0
		.amdhsa_tg_split 0
		.amdhsa_exception_fp_ieee_invalid_op 0
		.amdhsa_exception_fp_denorm_src 0
		.amdhsa_exception_fp_ieee_div_zero 0
		.amdhsa_exception_fp_ieee_overflow 0
		.amdhsa_exception_fp_ieee_underflow 0
		.amdhsa_exception_fp_ieee_inexact 0
		.amdhsa_exception_int_div_zero 0
	.end_amdhsa_kernel

amdhsa.kernels:
  - .agpr_count:     0
    .args:
      - .offset:         0
        .size:           264
        .value_kind:     by_value
      - .offset:         264
        .size:           4
        .value_kind:     hidden_block_count_x
      - .offset:         268
        .size:           4
        .value_kind:     hidden_block_count_y
      - .offset:         272
        .size:           4
        .value_kind:     hidden_block_count_z
      - .offset:         276
        .size:           2
        .value_kind:     hidden_group_size_x
      - .offset:         278
        .size:           2
        .value_kind:     hidden_group_size_y
      - .offset:         280
        .size:           2
        .value_kind:     hidden_group_size_z
      - .offset:         282
        .size:           2
        .value_kind:     hidden_remainder_x
      - .offset:         284
        .size:           2
        .value_kind:     hidden_remainder_y
      - .offset:         286
        .size:           2
        .value_kind:     hidden_remainder_z
      - .offset:         304
        .size:           8
        .value_kind:     hidden_global_offset_x
      - .offset:         312
        .size:           8
        .value_kind:     hidden_global_offset_y
      - .offset:         320
        .size:           8
        .value_kind:     hidden_global_offset_z
      - .offset:         328
        .size:           2
        .value_kind:     hidden_grid_dims
      - .offset:         384
        .size:           4
        .value_kind:     hidden_dynamic_lds_size
    .group_segment_fixed_size: 0
    .kernarg_segment_align: 8
    .kernarg_segment_size: 520
    .language:       OpenCL C
    .language_version:
      - 2
      - 0
    .max_flat_workgroup_size: 512
    .name:           _Z6mk_fwd7ParamsH
    .private_segment_fixed_size: 0
    .sgpr_count:     108
    .sgpr_spill_count: 231
    .symbol:         _Z6mk_fwd7ParamsH.kd
    .uniform_work_group_size: 1
    .uses_dynamic_stack: false
    .vgpr_count:     256
    .vgpr_spill_count: 0
    .wavefront_size: 64
